# MFMA/LDS interleave only in the P5 K-loop (A-fragment ds_reads of the second super-phase issued inside the preceding MFMA block); static priority in all K-loops
# speedup vs baseline: 1.0072x; 1.0017x over previous
; #define PG8_STAGE(bufoff, gbase, voff) do { _Pragma("unroll") for (int _i = 0; _i < 2; ++_i) \
;         __builtin_amdgcn_global_load_lds((const unsigned*)((const char*)(gbase) + (voff)[_i]), (PG8_LAS unsigned*)(lds + (bufoff) + ldsw + _i * 8192), 16, 0, 0); } while (0)
; #define PG8_LDA(dst, b, h) do { _Pragma("unroll") for (int m = 0; m < 4; ++m) _Pragma("unroll") for (int k = 0; k < 2; ++k) dst[m][k] = *(const PG8_LAS bf16x8*)(lds + PG8_SA(b, h) + aoff + m * 2048 + k * 1024); } while (0)
; #define PG8_LDB(dst, b, h) do { _Pragma("unroll") for (int n = 0; n < 2; ++n) _Pragma("unroll") for (int k = 0; k < 2; ++k) dst[n][k] = *(const PG8_LAS bf16x8*)(lds + PG8_SB(b, h) + boff + n * 2048 + k * 1024); } while (0)
; #define PG8_MMA(ai, bj, At, Bt) do { __builtin_amdgcn_s_setprio(1); _Pragma("unroll") for (int m = 0; m < 4; ++m) _Pragma("unroll") for (int n = 0; n < 2; ++n) _Pragma("unroll") for (int k = 0; k < 2; ++k) \
;         acc[ai][bj][m][n] = __builtin_amdgcn_mfma_f32_16x16x32_bf16(Bt[n][k], At[m][k], acc[ai][bj][m][n], 0, 0, 0); __builtin_amdgcn_s_setprio(0); } while (0)
; #define PG8_WAIT_V(n) asm volatile("s_waitcnt vmcnt(" #n ")" ::: "memory")
; #define PG8_WAIT_L(n) asm volatile("s_waitcnt lgkmcnt(" #n ")" ::: "memory")
; template <class Epi, class Sched, bool ALIGN_EPI = false, bool SP2 = false>
; __device__ __forceinline__ void gemm_phase(PG8_LAS unsigned char* lds, const Gemm g, const Sched& S, const Epi& E) {
;     ...
;             const bool last = (t == nt - 2);
;             const char* a1 = cA + (size_t)(t + 1) * kstep;
;             const char* a2 = last ? nA : cA + (size_t)(t + 2) * kstep; const char* b2 = last ? nB : cB + (size_t)(t + 2) * kstep;
;             const char* a3 = a2 + kstep; const char* b3 = b2 + kstep;
;             if (last && has_next) S.a_ready(nxt);
;             if constexpr (SP2) {
;             PG8_LDB(B0, 0, 0); PG8_LDB(B1, 0, 1); PG8_SCHED; PG8_LDA(At, 0, 0); PG8_STAGE(PG8_SA(1, 1), a1 + hstep, voffA);
;             PG8_WAIT_V(8); PG8_WAIT_L(0); PG8_BAR; PG8_MMA(0, 0, At, B0); PG8_MMA(0, 1, At, B1); PG8_BAR; PG8_SCHED;
;             PG8_LDA(At, 0, 1); PG8_STAGE(PG8_SB(0, 0), b2, voffB); PG8_STAGE(PG8_SB(0, 1), b2 + hstep, voffB); PG8_STAGE(PG8_SA(0, 0), a2, voffA);
;             PG8_WAIT_V(8); PG8_WAIT_L(0); PG8_BAR; PG8_MMA(1, 0, At, B0); PG8_MMA(1, 1, At, B1); PG8_BAR; PG8_SCHED;
.Lprio5_done:
.LBB0_574:
	ds_read_b128 v[128:131], v224
	ds_read_b128 v[132:135], v224 offset:1024
	ds_read_b128 v[136:139], v224 offset:2048
	ds_read_b128 v[140:143], v224 offset:3072
	ds_read_b128 v[144:147], v225
	ds_read_b128 v[148:151], v225 offset:1024
	ds_read_b128 v[152:155], v225 offset:2048
	ds_read_b128 v[156:159], v225 offset:3072
	s_add_u32 s0, s10, 0xfffc0080
	s_addc_u32 s1, s11, -1
	s_cmp_eq_u32 s21, 12
	s_cselect_b32 s15, s65, s1
	s_cselect_b32 s14, s64, s0
	s_cselect_b32 s13, s16, s20
	s_cselect_b32 s12, s17, s19
	v_lshl_add_u64 v[214:215], s[10:11], 0, v[186:187]
	s_add_i32 m0, s69, 0xc000
	ds_read_b128 v[160:163], v226
	ds_read_b128 v[164:167], v226 offset:1024
	ds_read_b128 v[168:171], v226 offset:2048
	ds_read_b128 v[172:175], v226 offset:3072
	ds_read_b128 v[196:199], v226 offset:4096
	ds_read_b128 v[200:203], v226 offset:5120
	ds_read_b128 v[204:207], v226 offset:6144
	ds_read_b128 v[210:213], v226 offset:7168
	global_load_lds_dwordx4 v[214:215], off
	v_lshl_add_u64 v[214:215], s[10:11], 0, v[188:189]
	s_add_i32 m0, s69, 0xe000
	s_nop 0
	global_load_lds_dwordx4 v[214:215], off
	s_waitcnt vmcnt(8)
	s_waitcnt lgkmcnt(0)
	s_barrier
	s_waitcnt lgkmcnt(0)
	v_mfma_f32_16x16x32_bf16 v[92:95], v[128:131], v[160:163], v[92:95]
	v_mfma_f32_16x16x32_bf16 v[44:47], v[136:139], v[160:163], v[44:47]
	v_mfma_f32_16x16x32_bf16 v[84:87], v[128:131], v[168:171], v[84:87]
	v_mfma_f32_16x16x32_bf16 v[36:39], v[136:139], v[168:171], v[36:39]
	v_mfma_f32_16x16x32_bf16 v[76:79], v[128:131], v[196:199], v[76:79]
	v_mfma_f32_16x16x32_bf16 v[28:31], v[136:139], v[196:199], v[28:31]
	v_mfma_f32_16x16x32_bf16 v[124:127], v[128:131], v[204:207], v[124:127]
	v_mfma_f32_16x16x32_bf16 v[120:123], v[136:139], v[204:207], v[120:123]
	v_mfma_f32_16x16x32_bf16 v[92:95], v[132:135], v[164:167], v[92:95]
	v_mfma_f32_16x16x32_bf16 v[44:47], v[140:143], v[164:167], v[44:47]
	v_mfma_f32_16x16x32_bf16 v[84:87], v[132:135], v[172:175], v[84:87]
	v_mfma_f32_16x16x32_bf16 v[36:39], v[140:143], v[172:175], v[36:39]
	v_mfma_f32_16x16x32_bf16 v[76:79], v[132:135], v[200:203], v[76:79]
	v_mfma_f32_16x16x32_bf16 v[28:31], v[140:143], v[200:203], v[28:31]
	v_mfma_f32_16x16x32_bf16 v[124:127], v[132:135], v[210:213], v[124:127]
	v_mfma_f32_16x16x32_bf16 v[120:123], v[140:143], v[210:213], v[120:123]
	v_mfma_f32_16x16x32_bf16 v[88:91], v[144:147], v[160:163], v[88:91]
	v_mfma_f32_16x16x32_bf16 v[40:43], v[152:155], v[160:163], v[40:43]
	ds_read_b128 v[160:163], v226 offset:16384
	v_mfma_f32_16x16x32_bf16 v[80:83], v[144:147], v[168:171], v[80:83]
	v_mfma_f32_16x16x32_bf16 v[32:35], v[152:155], v[168:171], v[32:35]
	ds_read_b128 v[168:171], v226 offset:18432
	v_mfma_f32_16x16x32_bf16 v[72:75], v[144:147], v[196:199], v[72:75]
	v_mfma_f32_16x16x32_bf16 v[24:27], v[152:155], v[196:199], v[24:27]
	ds_read_b128 v[196:199], v226 offset:20480
	v_mfma_f32_16x16x32_bf16 v[116:119], v[144:147], v[204:207], v[116:119]
	v_mfma_f32_16x16x32_bf16 v[112:115], v[152:155], v[204:207], v[112:115]
	ds_read_b128 v[204:207], v226 offset:22528
	v_mfma_f32_16x16x32_bf16 v[88:91], v[148:151], v[164:167], v[88:91]
	v_mfma_f32_16x16x32_bf16 v[40:43], v[156:159], v[164:167], v[40:43]
	ds_read_b128 v[164:167], v226 offset:17408
	v_mfma_f32_16x16x32_bf16 v[80:83], v[148:151], v[172:175], v[80:83]
	v_mfma_f32_16x16x32_bf16 v[32:35], v[156:159], v[172:175], v[32:35]
	ds_read_b128 v[172:175], v226 offset:19456
	v_mfma_f32_16x16x32_bf16 v[72:75], v[148:151], v[200:203], v[72:75]
	v_mfma_f32_16x16x32_bf16 v[24:27], v[156:159], v[200:203], v[24:27]
	ds_read_b128 v[200:203], v226 offset:21504
	v_mfma_f32_16x16x32_bf16 v[116:119], v[148:151], v[210:213], v[116:119]
	v_mfma_f32_16x16x32_bf16 v[112:115], v[156:159], v[210:213], v[112:115]
	ds_read_b128 v[210:213], v226 offset:23552
	s_barrier
	s_add_i32 s0, s97, s75
	v_lshl_add_u64 v[214:215], s[12:13], 0, v[178:179]
	s_mov_b32 m0, s0
	global_load_lds_dwordx4 v[214:215], off
	s_add_i32 m0, s0, 0x2000
	s_add_u32 s22, s12, 0x40000
	v_lshl_add_u64 v[216:217], s[12:13], 0, v[182:183]
	s_addc_u32 s23, s13, 0
	s_add_i32 s0, s72, s75
	global_load_lds_dwordx4 v[216:217], off
	v_lshl_add_u64 v[218:219], s[22:23], 0, v[178:179]
	s_mov_b32 m0, s0
	v_lshl_add_u64 v[220:221], s[14:15], 0, v[180:181]
	global_load_lds_dwordx4 v[218:219], off
	v_lshl_add_u64 v[218:219], s[22:23], 0, v[182:183]
	s_add_i32 m0, s0, 0x2000
	s_nop 0
	global_load_lds_dwordx4 v[218:219], off
	v_lshl_add_u64 v[218:219], s[14:15], 0, v[176:177]
	s_mov_b32 m0, s69
	s_nop 0
	global_load_lds_dwordx4 v[218:219], off
	s_mov_b32 m0, s76
	s_nop 0
	global_load_lds_dwordx4 v[220:221], off
	s_waitcnt vmcnt(8)
	s_waitcnt lgkmcnt(0)
	s_barrier
; #define PG8_STAGE(bufoff, gbase, voff) do { _Pragma("unroll") for (int _i = 0; _i < 2; ++_i) \
;         __builtin_amdgcn_global_load_lds((const unsigned*)((const char*)(gbase) + (voff)[_i]), (PG8_LAS unsigned*)(lds + (bufoff) + ldsw + _i * 8192), 16, 0, 0); } while (0)
; #define PG8_LDA(dst, b, h) do { _Pragma("unroll") for (int m = 0; m < 4; ++m) _Pragma("unroll") for (int k = 0; k < 2; ++k) dst[m][k] = *(const PG8_LAS bf16x8*)(lds + PG8_SA(b, h) + aoff + m * 2048 + k * 1024); } while (0)
; #define PG8_LDB(dst, b, h) do { _Pragma("unroll") for (int n = 0; n < 2; ++n) _Pragma("unroll") for (int k = 0; k < 2; ++k) dst[n][k] = *(const PG8_LAS bf16x8*)(lds + PG8_SB(b, h) + boff + n * 2048 + k * 1024); } while (0)
; #define PG8_MMA(ai, bj, At, Bt) do { __builtin_amdgcn_s_setprio(1); _Pragma("unroll") for (int m = 0; m < 4; ++m) _Pragma("unroll") for (int n = 0; n < 2; ++n) _Pragma("unroll") for (int k = 0; k < 2; ++k) \
;         acc[ai][bj][m][n] = __builtin_amdgcn_mfma_f32_16x16x32_bf16(Bt[n][k], At[m][k], acc[ai][bj][m][n], 0, 0, 0); __builtin_amdgcn_s_setprio(0); } while (0)
; #define PG8_WAIT_V(n) asm volatile("s_waitcnt vmcnt(" #n ")" ::: "memory")
; #define PG8_WAIT_L(n) asm volatile("s_waitcnt lgkmcnt(" #n ")" ::: "memory")
; #define PG8_BAR __builtin_amdgcn_s_barrier()
; #define PG8_SCHED __builtin_amdgcn_sched_barrier(0)
; template <class Epi, class Sched, bool ALIGN_EPI = false, bool SP2 = false>
; __device__ __forceinline__ void gemm_phase(PG8_LAS unsigned char* lds, const Gemm g, const Sched& S, const Epi& E) {
;     ...
;             PG8_WAIT_V(8); PG8_WAIT_L(0); PG8_BAR; PG8_MMA(1, 0, At, B0); PG8_MMA(1, 1, At, B1); PG8_BAR; PG8_SCHED;
;             PG8_LDB(B0, 1, 0); PG8_LDB(B1, 1, 1); PG8_SCHED; PG8_LDA(At, 1, 0); PG8_STAGE(PG8_SA(0, 1), a2 + hstep, voffA);
;             PG8_WAIT_V(8); PG8_WAIT_L(0); PG8_BAR; PG8_MMA(0, 0, At, B0); PG8_MMA(0, 1, At, B1); PG8_BAR; PG8_SCHED;
;             PG8_LDA(At, 1, 1); PG8_STAGE(PG8_SB(1, 0), b3, voffB); PG8_STAGE(PG8_SB(1, 1), b3 + hstep, voffB); PG8_STAGE(PG8_SA(1, 0), a3, voffA);
	s_waitcnt lgkmcnt(0)
	v_mfma_f32_16x16x32_bf16 v[68:71], v[128:131], v[160:163], v[68:71]
	v_mfma_f32_16x16x32_bf16 v[20:23], v[136:139], v[160:163], v[20:23]
	v_mfma_f32_16x16x32_bf16 v[60:63], v[128:131], v[168:171], v[60:63]
	v_mfma_f32_16x16x32_bf16 v[12:15], v[136:139], v[168:171], v[12:15]
	v_mfma_f32_16x16x32_bf16 v[52:55], v[128:131], v[196:199], v[52:55]
	v_mfma_f32_16x16x32_bf16 v[4:7], v[136:139], v[196:199], v[4:7]
	v_mfma_f32_16x16x32_bf16 v[108:111], v[128:131], v[204:207], v[108:111]
	v_mfma_f32_16x16x32_bf16 v[104:107], v[136:139], v[204:207], v[104:107]
	v_mfma_f32_16x16x32_bf16 v[68:71], v[132:135], v[164:167], v[68:71]
	v_mfma_f32_16x16x32_bf16 v[20:23], v[140:143], v[164:167], v[20:23]
	v_mfma_f32_16x16x32_bf16 v[60:63], v[132:135], v[172:175], v[60:63]
	v_mfma_f32_16x16x32_bf16 v[12:15], v[140:143], v[172:175], v[12:15]
	v_mfma_f32_16x16x32_bf16 v[52:55], v[132:135], v[200:203], v[52:55]
	v_mfma_f32_16x16x32_bf16 v[4:7], v[140:143], v[200:203], v[4:7]
	v_mfma_f32_16x16x32_bf16 v[108:111], v[132:135], v[210:213], v[108:111]
	v_mfma_f32_16x16x32_bf16 v[104:107], v[140:143], v[210:213], v[104:107]
	v_mfma_f32_16x16x32_bf16 v[64:67], v[144:147], v[160:163], v[64:67]
	v_mfma_f32_16x16x32_bf16 v[16:19], v[152:155], v[160:163], v[16:19]
	v_mfma_f32_16x16x32_bf16 v[56:59], v[144:147], v[168:171], v[56:59]
	v_mfma_f32_16x16x32_bf16 v[8:11], v[152:155], v[168:171], v[8:11]
	v_mfma_f32_16x16x32_bf16 v[48:51], v[144:147], v[196:199], v[48:51]
	v_mfma_f32_16x16x32_bf16 v[0:3], v[152:155], v[196:199], v[0:3]
	v_mfma_f32_16x16x32_bf16 v[100:103], v[144:147], v[204:207], v[100:103]
	v_mfma_f32_16x16x32_bf16 v[96:99], v[152:155], v[204:207], v[96:99]
	v_mfma_f32_16x16x32_bf16 v[64:67], v[148:151], v[164:167], v[64:67]
	v_mfma_f32_16x16x32_bf16 v[16:19], v[156:159], v[164:167], v[16:19]
	v_mfma_f32_16x16x32_bf16 v[56:59], v[148:151], v[172:175], v[56:59]
	v_mfma_f32_16x16x32_bf16 v[8:11], v[156:159], v[172:175], v[8:11]
	v_mfma_f32_16x16x32_bf16 v[48:51], v[148:151], v[200:203], v[48:51]
	v_mfma_f32_16x16x32_bf16 v[0:3], v[156:159], v[200:203], v[0:3]
	v_mfma_f32_16x16x32_bf16 v[100:103], v[148:151], v[210:213], v[100:103]
	v_mfma_f32_16x16x32_bf16 v[96:99], v[156:159], v[210:213], v[96:99]
	s_barrier
	s_add_i32 s0, 0, 0x18000
	s_add_i32 s1, 0, 0x1c000
	v_add_u32_e32 v140, s0, v223
	v_add_u32_e32 v156, s1, v223
	ds_read_b128 v[128:131], v140
	ds_read_b128 v[132:135], v140 offset:1024
	ds_read_b128 v[136:139], v140 offset:2048
	ds_read_b128 v[140:143], v140 offset:3072
	ds_read_b128 v[144:147], v156
	ds_read_b128 v[148:151], v156 offset:1024
	ds_read_b128 v[152:155], v156 offset:2048
	ds_read_b128 v[156:159], v156 offset:3072
	s_add_u32 s14, s14, 0x40000
	s_addc_u32 s15, s15, 0
	s_mov_b32 m0, s77
	v_lshl_add_u64 v[228:229], s[14:15], 0, v[176:177]
	ds_read_b128 v[160:163], v226 offset:32768
	ds_read_b128 v[164:167], v226 offset:33792
	ds_read_b128 v[168:171], v226 offset:34816
	ds_read_b128 v[172:175], v226 offset:35840
	ds_read_b128 v[196:199], v226 offset:36864
	ds_read_b128 v[200:203], v226 offset:37888
	ds_read_b128 v[204:207], v226 offset:38912
	ds_read_b128 v[210:213], v226 offset:39936
	global_load_lds_dwordx4 v[228:229], off
	v_lshl_add_u64 v[228:229], s[14:15], 0, v[180:181]
	s_mov_b32 m0, s78
	s_nop 0
	global_load_lds_dwordx4 v[228:229], off
	s_waitcnt vmcnt(8)
	s_waitcnt lgkmcnt(0)
	s_barrier
	s_waitcnt lgkmcnt(0)
	v_mfma_f32_16x16x32_bf16 v[92:95], v[128:131], v[160:163], v[92:95]
	v_mfma_f32_16x16x32_bf16 v[44:47], v[136:139], v[160:163], v[44:47]
	v_mfma_f32_16x16x32_bf16 v[84:87], v[128:131], v[168:171], v[84:87]
	v_mfma_f32_16x16x32_bf16 v[36:39], v[136:139], v[168:171], v[36:39]
	v_mfma_f32_16x16x32_bf16 v[76:79], v[128:131], v[196:199], v[76:79]
	v_mfma_f32_16x16x32_bf16 v[28:31], v[136:139], v[196:199], v[28:31]
	v_mfma_f32_16x16x32_bf16 v[124:127], v[128:131], v[204:207], v[124:127]
	v_mfma_f32_16x16x32_bf16 v[120:123], v[136:139], v[204:207], v[120:123]
	v_mfma_f32_16x16x32_bf16 v[92:95], v[132:135], v[164:167], v[92:95]
	v_mfma_f32_16x16x32_bf16 v[44:47], v[140:143], v[164:167], v[44:47]
	v_mfma_f32_16x16x32_bf16 v[84:87], v[132:135], v[172:175], v[84:87]
	v_mfma_f32_16x16x32_bf16 v[36:39], v[140:143], v[172:175], v[36:39]
	v_mfma_f32_16x16x32_bf16 v[76:79], v[132:135], v[200:203], v[76:79]
	v_mfma_f32_16x16x32_bf16 v[28:31], v[140:143], v[200:203], v[28:31]
	v_mfma_f32_16x16x32_bf16 v[124:127], v[132:135], v[210:213], v[124:127]
	v_mfma_f32_16x16x32_bf16 v[120:123], v[140:143], v[210:213], v[120:123]
	v_mfma_f32_16x16x32_bf16 v[88:91], v[144:147], v[160:163], v[88:91]
	v_mfma_f32_16x16x32_bf16 v[40:43], v[152:155], v[160:163], v[40:43]
	ds_read_b128 v[160:163], v226 offset:49152
	v_mfma_f32_16x16x32_bf16 v[80:83], v[144:147], v[168:171], v[80:83]
	v_mfma_f32_16x16x32_bf16 v[32:35], v[152:155], v[168:171], v[32:35]
	ds_read_b128 v[168:171], v226 offset:51200
	v_mfma_f32_16x16x32_bf16 v[72:75], v[144:147], v[196:199], v[72:75]
	v_mfma_f32_16x16x32_bf16 v[24:27], v[152:155], v[196:199], v[24:27]
	ds_read_b128 v[196:199], v226 offset:53248
	v_mfma_f32_16x16x32_bf16 v[116:119], v[144:147], v[204:207], v[116:119]
	v_mfma_f32_16x16x32_bf16 v[112:115], v[152:155], v[204:207], v[112:115]
	ds_read_b128 v[204:207], v226 offset:55296
	v_mfma_f32_16x16x32_bf16 v[88:91], v[148:151], v[164:167], v[88:91]
	v_mfma_f32_16x16x32_bf16 v[40:43], v[156:159], v[164:167], v[40:43]
	ds_read_b128 v[164:167], v226 offset:50176
	v_mfma_f32_16x16x32_bf16 v[80:83], v[148:151], v[172:175], v[80:83]
	v_mfma_f32_16x16x32_bf16 v[32:35], v[156:159], v[172:175], v[32:35]
	ds_read_b128 v[172:175], v226 offset:52224
	v_mfma_f32_16x16x32_bf16 v[72:75], v[148:151], v[200:203], v[72:75]
	v_mfma_f32_16x16x32_bf16 v[24:27], v[156:159], v[200:203], v[24:27]
	ds_read_b128 v[200:203], v226 offset:54272
	v_mfma_f32_16x16x32_bf16 v[116:119], v[148:151], v[210:213], v[116:119]
	v_mfma_f32_16x16x32_bf16 v[112:115], v[156:159], v[210:213], v[112:115]
	ds_read_b128 v[210:213], v226 offset:56320
	s_barrier
; #define PG8_STAGE(bufoff, gbase, voff) do { _Pragma("unroll") for (int _i = 0; _i < 2; ++_i) \
;         __builtin_amdgcn_global_load_lds((const unsigned*)((const char*)(gbase) + (voff)[_i]), (PG8_LAS unsigned*)(lds + (bufoff) + ldsw + _i * 8192), 16, 0, 0); } while (0)
; #define PG8_LDA(dst, b, h) do { _Pragma("unroll") for (int m = 0; m < 4; ++m) _Pragma("unroll") for (int k = 0; k < 2; ++k) dst[m][k] = *(const PG8_LAS bf16x8*)(lds + PG8_SA(b, h) + aoff + m * 2048 + k * 1024); } while (0)
; #define PG8_MMA(ai, bj, At, Bt) do { __builtin_amdgcn_s_setprio(1); _Pragma("unroll") for (int m = 0; m < 4; ++m) _Pragma("unroll") for (int n = 0; n < 2; ++n) _Pragma("unroll") for (int k = 0; k < 2; ++k) \
;         acc[ai][bj][m][n] = __builtin_amdgcn_mfma_f32_16x16x32_bf16(Bt[n][k], At[m][k], acc[ai][bj][m][n], 0, 0, 0); __builtin_amdgcn_s_setprio(0); } while (0)
; #define PG8_WAIT_V(n) asm volatile("s_waitcnt vmcnt(" #n ")" ::: "memory")
; #define PG8_WAIT_L(n) asm volatile("s_waitcnt lgkmcnt(" #n ")" ::: "memory")
; #define PG8_BAR __builtin_amdgcn_s_barrier()
; #define PG8_SCHED __builtin_amdgcn_sched_barrier(0)
; template <class Epi, class Sched, bool ALIGN_EPI = false, bool SP2 = false>
; __device__ __forceinline__ void gemm_phase(PG8_LAS unsigned char* lds, const Gemm g, const Sched& S, const Epi& E) {
;     ...
;             PG8_LDA(At, 1, 1); PG8_STAGE(PG8_SB(1, 0), b3, voffB); PG8_STAGE(PG8_SB(1, 1), b3 + hstep, voffB); PG8_STAGE(PG8_SA(1, 0), a3, voffA);
;             PG8_WAIT_V(8); PG8_WAIT_L(0); PG8_BAR; PG8_MMA(1, 0, At, B0); PG8_MMA(1, 1, At, B1); PG8_BAR; PG8_SCHED;
	s_add_i32 s0, s0, s75
	v_lshl_add_u64 v[214:215], v[214:215], 0, s[40:41]
	s_mov_b32 m0, s0
	global_load_lds_dwordx4 v[214:215], off
	s_add_i32 m0, s0, 0x2000
	s_add_u32 s12, s12, 0x40080
	v_lshl_add_u64 v[214:215], v[216:217], 0, s[40:41]
	s_addc_u32 s13, s13, 0
	s_add_i32 s0, s1, s75
	global_load_lds_dwordx4 v[214:215], off
	v_lshl_add_u64 v[214:215], s[12:13], 0, v[178:179]
	s_mov_b32 m0, s0
	s_nop 0
	global_load_lds_dwordx4 v[214:215], off
	v_lshl_add_u64 v[214:215], s[12:13], 0, v[182:183]
	s_add_i32 m0, s0, 0x2000
	s_nop 0
	global_load_lds_dwordx4 v[214:215], off
	v_lshl_add_u64 v[214:215], v[218:219], 0, s[40:41]
	s_mov_b32 m0, s85
	s_nop 0
	global_load_lds_dwordx4 v[214:215], off
	v_lshl_add_u64 v[214:215], v[220:221], 0, s[40:41]
	s_mov_b32 m0, s86
	s_nop 0
	global_load_lds_dwordx4 v[214:215], off
	s_waitcnt vmcnt(8)
	s_waitcnt lgkmcnt(0)
	s_barrier
	s_waitcnt lgkmcnt(0)
	v_mfma_f32_16x16x32_bf16 v[68:71], v[128:131], v[160:163], v[68:71]
	v_mfma_f32_16x16x32_bf16 v[20:23], v[136:139], v[160:163], v[20:23]
	v_mfma_f32_16x16x32_bf16 v[60:63], v[128:131], v[168:171], v[60:63]
	v_mfma_f32_16x16x32_bf16 v[12:15], v[136:139], v[168:171], v[12:15]
	v_mfma_f32_16x16x32_bf16 v[52:55], v[128:131], v[196:199], v[52:55]
	v_mfma_f32_16x16x32_bf16 v[4:7], v[136:139], v[196:199], v[4:7]
	v_mfma_f32_16x16x32_bf16 v[108:111], v[128:131], v[204:207], v[108:111]
	v_mfma_f32_16x16x32_bf16 v[104:107], v[136:139], v[204:207], v[104:107]
	v_mfma_f32_16x16x32_bf16 v[68:71], v[132:135], v[164:167], v[68:71]
	v_mfma_f32_16x16x32_bf16 v[20:23], v[140:143], v[164:167], v[20:23]
	v_mfma_f32_16x16x32_bf16 v[60:63], v[132:135], v[172:175], v[60:63]
	v_mfma_f32_16x16x32_bf16 v[12:15], v[140:143], v[172:175], v[12:15]
	v_mfma_f32_16x16x32_bf16 v[52:55], v[132:135], v[200:203], v[52:55]
	v_mfma_f32_16x16x32_bf16 v[4:7], v[140:143], v[200:203], v[4:7]
	v_mfma_f32_16x16x32_bf16 v[108:111], v[132:135], v[210:213], v[108:111]
	v_mfma_f32_16x16x32_bf16 v[104:107], v[140:143], v[210:213], v[104:107]
	v_mfma_f32_16x16x32_bf16 v[64:67], v[144:147], v[160:163], v[64:67]
	v_mfma_f32_16x16x32_bf16 v[16:19], v[152:155], v[160:163], v[16:19]
	v_mfma_f32_16x16x32_bf16 v[56:59], v[144:147], v[168:171], v[56:59]
	v_mfma_f32_16x16x32_bf16 v[8:11], v[152:155], v[168:171], v[8:11]
	v_mfma_f32_16x16x32_bf16 v[48:51], v[144:147], v[196:199], v[48:51]
	v_mfma_f32_16x16x32_bf16 v[0:3], v[152:155], v[196:199], v[0:3]
	v_mfma_f32_16x16x32_bf16 v[100:103], v[144:147], v[204:207], v[100:103]
	v_mfma_f32_16x16x32_bf16 v[96:99], v[152:155], v[204:207], v[96:99]
	v_mfma_f32_16x16x32_bf16 v[64:67], v[148:151], v[164:167], v[64:67]
	v_mfma_f32_16x16x32_bf16 v[16:19], v[156:159], v[164:167], v[16:19]
	v_mfma_f32_16x16x32_bf16 v[56:59], v[148:151], v[172:175], v[56:59]
	v_mfma_f32_16x16x32_bf16 v[8:11], v[156:159], v[172:175], v[8:11]
	v_mfma_f32_16x16x32_bf16 v[48:51], v[148:151], v[200:203], v[48:51]
	v_mfma_f32_16x16x32_bf16 v[0:3], v[156:159], v[200:203], v[0:3]
	v_mfma_f32_16x16x32_bf16 v[100:103], v[148:151], v[210:213], v[100:103]
	v_mfma_f32_16x16x32_bf16 v[96:99], v[156:159], v[210:213], v[96:99]
	s_barrier
	s_add_i32 s21, s21, 2
	s_add_u32 s10, s10, 0x100
	s_addc_u32 s11, s11, 0
	s_add_u32 s19, s19, 0x100
	s_addc_u32 s20, s20, 0
	s_cmp_gt_u32 s21, 13
	s_cbranch_scc0 .LBB0_574
	s_setprio 0
	s_and_b64 vcc, exec, s[42:43]
	s_cbranch_vccnz .LBB0_579
	s_cmp_lg_u32 s18, 64
	s_mov_b64 s[10:11], -1
	s_cbranch_scc1 .LBB0_580
